# P6 panel exchange: partial row sums published with a ready flag in the mantissa LSB into slots zeroed at kernel entry; row owners poll their own 8 slots with two sc1 dwordx4 loads (no store-ack wait,
# speedup vs baseline: 1.0040x; 1.0037x over previous
_Z6mk_fwd4Args:
	s_load_dwordx16 s[48:63], s[0:1], 0x80
	s_load_dwordx4 s[80:83], s[0:1], 0xc0
	s_add_u32 s6, s0, 0xc8
	v_and_b32_e32 v144, 0x3ff, v0
	s_addc_u32 s7, s1, 0
	v_readfirstlane_b32 s91, v144
	v_cmp_gt_u32_e32 vcc, 16, v144
	s_and_saveexec_b64 s[4:5], vcc
	v_lshl_add_u32 v1, v144, 2, 0
	v_add_u32_e32 v1, 0x23fc0, v1
	v_mov_b32_e32 v2, 0
	ds_write_b32 v1, v2
	s_or_b64 exec, exec, s[4:5]
	s_load_dword s90, s[0:1], 0xd0
	s_waitcnt lgkmcnt(0)
	s_barrier
	s_lshl_b32 s100, s2, 12
	v_lshl_add_u32 v1, v144, 3, s100
	v_mov_b32_e32 v2, 0
	v_mov_b32_e32 v3, 0
	s_add_u32 s100, s62, 0x3400000
	s_addc_u32 s101, s63, 0
	global_store_dwordx2 v1, v[2:3], s[100:101]
	s_nop 0
	s_nop 0
	s_nop 0
	s_nop 0
	s_nop 0
	s_nop 0
	s_add_u32 s46, s62, 0x3300000
	s_getreg_b32 s3, hwreg(HW_REG_XCC_ID, 0, 4)
	s_addc_u32 s47, s63, 0
	s_and_b32 s33, s3, 15
	v_cmp_eq_u32_e64 s[44:45], 0, v144
	s_and_saveexec_b64 s[4:5], s[44:45]
	s_cbranch_execz .LBB0_5
	s_mov_b64 s[8:9], exec
	v_mbcnt_lo_u32_b32 v1, s8, 0
	v_mbcnt_hi_u32_b32 v1, s9, v1
	v_cmp_eq_u32_e32 vcc, 0, v1
	s_and_b64 s[10:11], exec, vcc
	s_mov_b64 exec, s[10:11]
	s_cbranch_execz .LBB0_5
	s_lshl_b32 s3, s33, 8
	s_bcnt1_i32_b64 s8, s[8:9]
	v_mov_b32_e32 v1, s3
	v_mov_b32_e32 v2, s8
	global_atomic_add v1, v2, s[46:47] offset:1024

.LBB0_532:
	s_nop 7
	v_lshrrev_b32_e32 v224, 2, v193
	v_and_b32_e32 v225, 3, v193
	v_lshl_add_u32 v224, v225, 4, v224
	v_lshlrev_b32_e32 v224, 2, v224
	ds_bpermute_b32 v0, v224, v0
	ds_bpermute_b32 v1, v224, v1
	ds_bpermute_b32 v2, v224, v2
	ds_bpermute_b32 v3, v224, v3
	ds_bpermute_b32 v4, v224, v4
	ds_bpermute_b32 v5, v224, v5
	ds_bpermute_b32 v6, v224, v6
	ds_bpermute_b32 v7, v224, v7
	ds_bpermute_b32 v8, v224, v8
	ds_bpermute_b32 v9, v224, v9
	ds_bpermute_b32 v10, v224, v10
	ds_bpermute_b32 v11, v224, v11
	ds_bpermute_b32 v12, v224, v12
	ds_bpermute_b32 v13, v224, v13
	ds_bpermute_b32 v14, v224, v14
	ds_bpermute_b32 v15, v224, v15
	ds_bpermute_b32 v16, v224, v16
	ds_bpermute_b32 v17, v224, v17
	ds_bpermute_b32 v18, v224, v18
	ds_bpermute_b32 v19, v224, v19
	ds_bpermute_b32 v20, v224, v20
	ds_bpermute_b32 v21, v224, v21
	ds_bpermute_b32 v22, v224, v22
	ds_bpermute_b32 v23, v224, v23
	ds_bpermute_b32 v24, v224, v24
	ds_bpermute_b32 v25, v224, v25
	ds_bpermute_b32 v26, v224, v26
	ds_bpermute_b32 v27, v224, v27
	ds_bpermute_b32 v28, v224, v28
	ds_bpermute_b32 v29, v224, v29
	ds_bpermute_b32 v30, v224, v30
	ds_bpermute_b32 v31, v224, v31
	ds_bpermute_b32 v32, v224, v32
	ds_bpermute_b32 v33, v224, v33
	ds_bpermute_b32 v34, v224, v34
	ds_bpermute_b32 v35, v224, v35
	ds_bpermute_b32 v36, v224, v36
	ds_bpermute_b32 v37, v224, v37
	ds_bpermute_b32 v38, v224, v38
	ds_bpermute_b32 v39, v224, v39
	ds_bpermute_b32 v40, v224, v40
	ds_bpermute_b32 v41, v224, v41
	ds_bpermute_b32 v42, v224, v42
	ds_bpermute_b32 v43, v224, v43
	ds_bpermute_b32 v44, v224, v44
	ds_bpermute_b32 v45, v224, v45
	ds_bpermute_b32 v46, v224, v46
	ds_bpermute_b32 v47, v224, v47
	ds_bpermute_b32 v48, v224, v48
	ds_bpermute_b32 v49, v224, v49
	ds_bpermute_b32 v50, v224, v50
	ds_bpermute_b32 v51, v224, v51
	ds_bpermute_b32 v52, v224, v52
	ds_bpermute_b32 v53, v224, v53
	ds_bpermute_b32 v54, v224, v54
	ds_bpermute_b32 v55, v224, v55
	ds_bpermute_b32 v56, v224, v56
	ds_bpermute_b32 v57, v224, v57
	ds_bpermute_b32 v58, v224, v58
	ds_bpermute_b32 v59, v224, v59
	ds_bpermute_b32 v60, v224, v60
	ds_bpermute_b32 v61, v224, v61
	ds_bpermute_b32 v62, v224, v62
	ds_bpermute_b32 v63, v224, v63
	ds_bpermute_b32 v64, v224, v64
	ds_bpermute_b32 v65, v224, v65
	ds_bpermute_b32 v66, v224, v66
	ds_bpermute_b32 v67, v224, v67
	ds_bpermute_b32 v68, v224, v68
	ds_bpermute_b32 v69, v224, v69
	ds_bpermute_b32 v70, v224, v70
	ds_bpermute_b32 v71, v224, v71
	ds_bpermute_b32 v72, v224, v72
	ds_bpermute_b32 v73, v224, v73
	ds_bpermute_b32 v74, v224, v74
	ds_bpermute_b32 v75, v224, v75
	ds_bpermute_b32 v76, v224, v76
	ds_bpermute_b32 v77, v224, v77
	ds_bpermute_b32 v78, v224, v78
	ds_bpermute_b32 v79, v224, v79
	ds_bpermute_b32 v80, v224, v80
	ds_bpermute_b32 v81, v224, v81
	ds_bpermute_b32 v82, v224, v82
	ds_bpermute_b32 v83, v224, v83
	ds_bpermute_b32 v84, v224, v84
	ds_bpermute_b32 v85, v224, v85
	ds_bpermute_b32 v86, v224, v86
	ds_bpermute_b32 v87, v224, v87
	ds_bpermute_b32 v88, v224, v88
	ds_bpermute_b32 v89, v224, v89
	ds_bpermute_b32 v90, v224, v90
	ds_bpermute_b32 v91, v224, v91
	ds_bpermute_b32 v92, v224, v92
	ds_bpermute_b32 v93, v224, v93
	ds_bpermute_b32 v94, v224, v94
	ds_bpermute_b32 v95, v224, v95
	ds_bpermute_b32 v112, v224, v112
	ds_bpermute_b32 v113, v224, v113
	ds_bpermute_b32 v114, v224, v114
	ds_bpermute_b32 v115, v224, v115
	ds_bpermute_b32 v116, v224, v116
	ds_bpermute_b32 v117, v224, v117
	ds_bpermute_b32 v118, v224, v118
	ds_bpermute_b32 v119, v224, v119
	ds_bpermute_b32 v120, v224, v120
	ds_bpermute_b32 v121, v224, v121
	ds_bpermute_b32 v122, v224, v122
	ds_bpermute_b32 v123, v224, v123
	ds_bpermute_b32 v124, v224, v124
	ds_bpermute_b32 v125, v224, v125
	ds_bpermute_b32 v126, v224, v126
	ds_bpermute_b32 v127, v224, v127
	ds_bpermute_b32 v128, v224, v128
	ds_bpermute_b32 v129, v224, v129
	ds_bpermute_b32 v130, v224, v130
	ds_bpermute_b32 v131, v224, v131
	ds_bpermute_b32 v132, v224, v132
	ds_bpermute_b32 v133, v224, v133
	ds_bpermute_b32 v134, v224, v134
	ds_bpermute_b32 v135, v224, v135
	ds_bpermute_b32 v136, v224, v136
	ds_bpermute_b32 v137, v224, v137
	ds_bpermute_b32 v138, v224, v138
	ds_bpermute_b32 v139, v224, v139
	ds_bpermute_b32 v140, v224, v140
	ds_bpermute_b32 v141, v224, v141
	ds_bpermute_b32 v142, v224, v142
	ds_bpermute_b32 v143, v224, v143
	s_waitcnt lgkmcnt(0)
	v_and_b32_e32 v175, 3, v193
	v_lshrrev_b32_e32 v96, 2, v193
	v_mov_b32_e32 v185, v193
	s_lshl_b32 s26, s67, 8
	v_add_u32_e32 v194, s49, v96
	v_add_u32_e32 v195, s26, v194
	v_lshl_add_u32 v156, v175, 2, s53
	v_lshlrev_b32_e32 v156, 2, v156
	v_mov_b32_e32 v157, 0
	s_lshr_b32 s84, s67, 6
	s_lshl_b32 s84, s84, 13
	s_add_u32 s84, s39, s84
	s_addc_u32 s85, s40, 0
	s_add_u32 s86, s10, 0x20000
	s_addc_u32 s87, s11, 0
	s_add_u32 s88, s10, 0x40000
	s_addc_u32 s89, s11, 0
	global_load_dwordx4 v[104:107], v156, s[84:85]
	global_load_dwordx4 v[100:103], v156, s[84:85] offset:64
	global_load_dwordx4 v[96:99], v156, s[84:85] offset:512
	global_load_dwordx4 v[108:111], v156, s[84:85] offset:576
	v_mov_b32_e32 v242, v195
	v_lshlrev_b32_e32 v243, 2, v242
	v_lshl_add_u32 v244, v242, 13, v156
	global_load_dword v228, v243, s[10:11]
	global_load_dword v229, v243, s[86:87]
	global_load_dword v230, v243, s[88:89]
	global_load_dwordx4 v[160:163], v244, s[64:65] nt
	global_load_dwordx4 v[164:167], v244, s[64:65] offset:64 nt
	global_load_dwordx4 v[168:171], v244, s[64:65] offset:512 nt
	global_load_dwordx4 v[172:175], v244, s[64:65] offset:576 nt
	v_add_u32_e32 v242, 16, v195
	v_lshlrev_b32_e32 v243, 2, v242
	v_lshl_add_u32 v244, v242, 13, v156
	global_load_dword v231, v243, s[10:11]
	global_load_dword v232, v243, s[86:87]
	global_load_dword v233, v243, s[88:89]
	global_load_dwordx4 v[196:199], v244, s[64:65] nt
	global_load_dwordx4 v[200:203], v244, s[64:65] offset:64 nt
	global_load_dwordx4 v[204:207], v244, s[64:65] offset:512 nt
	global_load_dwordx4 v[208:211], v244, s[64:65] offset:576 nt
	v_add_u32_e32 v242, 32, v195
	v_lshlrev_b32_e32 v243, 2, v242
	v_lshl_add_u32 v244, v242, 13, v156
	global_load_dword v234, v243, s[10:11]
	global_load_dword v235, v243, s[86:87]
	global_load_dword v236, v243, s[88:89]
	global_load_dwordx4 v[212:215], v244, s[64:65] nt
	global_load_dwordx4 v[216:219], v244, s[64:65] offset:64 nt
	global_load_dwordx4 v[220:223], v244, s[64:65] offset:512 nt
	global_load_dwordx4 v[224:227], v244, s[64:65] offset:576 nt
	s_waitcnt vmcnt(14)
	v_add_f32_e32 v238, v228, v229
	v_add_f32_e32 v238, v238, v230
	v_fmamk_f32 v238, v238, 0x3a2aaaab, v183
	v_rsq_f32_e32 v238, v238
	s_nop 0
	v_pk_mul_f32 v[140:141], v[140:141], v[238:239] op_sel_hi:[1,0]
	v_pk_mul_f32 v[142:143], v[142:143], v[238:239] op_sel_hi:[1,0]
	v_pk_fma_f32 v[140:141], v[104:105], v[140:141], v[160:161]
	v_pk_fma_f32 v[142:143], v[106:107], v[142:143], v[162:163]
	v_pk_mul_f32 v[136:137], v[136:137], v[238:239] op_sel_hi:[1,0]
	v_pk_mul_f32 v[138:139], v[138:139], v[238:239] op_sel_hi:[1,0]
	v_pk_fma_f32 v[136:137], v[100:101], v[136:137], v[164:165]
	v_pk_fma_f32 v[138:139], v[102:103], v[138:139], v[166:167]
	v_pk_mul_f32 v[132:133], v[132:133], v[238:239] op_sel_hi:[1,0]
	v_pk_mul_f32 v[134:135], v[134:135], v[238:239] op_sel_hi:[1,0]
	v_pk_fma_f32 v[132:133], v[96:97], v[132:133], v[168:169]
	v_pk_fma_f32 v[134:135], v[98:99], v[134:135], v[170:171]
	v_pk_mul_f32 v[128:129], v[128:129], v[238:239] op_sel_hi:[1,0]
	v_pk_mul_f32 v[130:131], v[130:131], v[238:239] op_sel_hi:[1,0]
	v_pk_fma_f32 v[128:129], v[108:109], v[128:129], v[172:173]
	v_pk_fma_f32 v[130:131], v[110:111], v[130:131], v[174:175]
	v_pk_mul_f32 v[240:241], v[140:141], v[140:141]
	v_pk_fma_f32 v[240:241], v[142:143], v[142:143], v[240:241]
	v_pk_fma_f32 v[240:241], v[136:137], v[136:137], v[240:241]
	v_pk_fma_f32 v[240:241], v[138:139], v[138:139], v[240:241]
	v_pk_fma_f32 v[240:241], v[132:133], v[132:133], v[240:241]
	v_pk_fma_f32 v[240:241], v[134:135], v[134:135], v[240:241]
	v_pk_fma_f32 v[240:241], v[128:129], v[128:129], v[240:241]
	v_pk_fma_f32 v[240:241], v[130:131], v[130:131], v[240:241]
	v_add_f32_e32 v240, v240, v241
	v_mov_b32_e32 v245, v194
	v_lshl_add_u32 v245, v245, 4, s51
	v_add_f32_dpp v240, v240, v240 quad_perm:[1,0,3,2] row_mask:0xf bank_mask:0xf
	s_nop 1
	v_add_f32_dpp v240, v240, v240 quad_perm:[2,3,0,1] row_mask:0xf bank_mask:0xf
	ds_write_b32 v245, v240
	v_add_u32_e32 v242, 48, v195
	v_lshlrev_b32_e32 v243, 2, v242
	v_lshl_add_u32 v244, v242, 13, v156
	global_load_dword v228, v243, s[10:11]
	global_load_dword v229, v243, s[86:87]
	global_load_dword v230, v243, s[88:89]
	global_load_dwordx4 v[160:163], v244, s[64:65] nt
	global_load_dwordx4 v[164:167], v244, s[64:65] offset:64 nt
	global_load_dwordx4 v[168:171], v244, s[64:65] offset:512 nt
	global_load_dwordx4 v[172:175], v244, s[64:65] offset:576 nt
	s_waitcnt vmcnt(14)
	v_add_f32_e32 v238, v231, v232
	v_add_f32_e32 v238, v238, v233
	v_fmamk_f32 v238, v238, 0x3a2aaaab, v183
	v_rsq_f32_e32 v238, v238
	s_nop 0
	v_pk_mul_f32 v[124:125], v[124:125], v[238:239] op_sel_hi:[1,0]
	v_pk_mul_f32 v[126:127], v[126:127], v[238:239] op_sel_hi:[1,0]
	v_pk_fma_f32 v[124:125], v[104:105], v[124:125], v[196:197]
	v_pk_fma_f32 v[126:127], v[106:107], v[126:127], v[198:199]
	v_pk_mul_f32 v[120:121], v[120:121], v[238:239] op_sel_hi:[1,0]
	v_pk_mul_f32 v[122:123], v[122:123], v[238:239] op_sel_hi:[1,0]
	v_pk_fma_f32 v[120:121], v[100:101], v[120:121], v[200:201]
	v_pk_fma_f32 v[122:123], v[102:103], v[122:123], v[202:203]
	v_pk_mul_f32 v[116:117], v[116:117], v[238:239] op_sel_hi:[1,0]
	v_pk_mul_f32 v[118:119], v[118:119], v[238:239] op_sel_hi:[1,0]
	v_pk_fma_f32 v[116:117], v[96:97], v[116:117], v[204:205]
	v_pk_fma_f32 v[118:119], v[98:99], v[118:119], v[206:207]
	v_pk_mul_f32 v[112:113], v[112:113], v[238:239] op_sel_hi:[1,0]
	v_pk_mul_f32 v[114:115], v[114:115], v[238:239] op_sel_hi:[1,0]
	v_pk_fma_f32 v[112:113], v[108:109], v[112:113], v[208:209]
	v_pk_fma_f32 v[114:115], v[110:111], v[114:115], v[210:211]
	v_pk_mul_f32 v[240:241], v[124:125], v[124:125]
	v_pk_fma_f32 v[240:241], v[126:127], v[126:127], v[240:241]
	v_pk_fma_f32 v[240:241], v[120:121], v[120:121], v[240:241]
	v_pk_fma_f32 v[240:241], v[122:123], v[122:123], v[240:241]
	v_pk_fma_f32 v[240:241], v[116:117], v[116:117], v[240:241]
	v_pk_fma_f32 v[240:241], v[118:119], v[118:119], v[240:241]
	v_pk_fma_f32 v[240:241], v[112:113], v[112:113], v[240:241]
	v_pk_fma_f32 v[240:241], v[114:115], v[114:115], v[240:241]
	v_add_f32_e32 v240, v240, v241
	v_add_u32_e32 v245, 16, v194
	v_lshl_add_u32 v245, v245, 4, s51
	v_add_f32_dpp v240, v240, v240 quad_perm:[1,0,3,2] row_mask:0xf bank_mask:0xf
	s_nop 1
	v_add_f32_dpp v240, v240, v240 quad_perm:[2,3,0,1] row_mask:0xf bank_mask:0xf
	ds_write_b32 v245, v240
	v_add_u32_e32 v242, 128, v195
	v_lshlrev_b32_e32 v243, 2, v242
	v_lshl_add_u32 v244, v242, 13, v156
	global_load_dword v231, v243, s[10:11]
	global_load_dword v232, v243, s[86:87]
	global_load_dword v233, v243, s[88:89]
	global_load_dwordx4 v[196:199], v244, s[64:65] nt
	global_load_dwordx4 v[200:203], v244, s[64:65] offset:64 nt
	global_load_dwordx4 v[204:207], v244, s[64:65] offset:512 nt
	global_load_dwordx4 v[208:211], v244, s[64:65] offset:576 nt
	s_waitcnt vmcnt(14)
	v_add_f32_e32 v238, v234, v235
	v_add_f32_e32 v238, v238, v236
	v_fmamk_f32 v238, v238, 0x3a2aaaab, v183
	v_rsq_f32_e32 v238, v238
	s_nop 0
	v_pk_mul_f32 v[92:93], v[92:93], v[238:239] op_sel_hi:[1,0]
	v_pk_mul_f32 v[94:95], v[94:95], v[238:239] op_sel_hi:[1,0]
	v_pk_fma_f32 v[92:93], v[104:105], v[92:93], v[212:213]
	v_pk_fma_f32 v[94:95], v[106:107], v[94:95], v[214:215]
	v_pk_mul_f32 v[88:89], v[88:89], v[238:239] op_sel_hi:[1,0]
	v_pk_mul_f32 v[90:91], v[90:91], v[238:239] op_sel_hi:[1,0]
	v_pk_fma_f32 v[88:89], v[100:101], v[88:89], v[216:217]
	v_pk_fma_f32 v[90:91], v[102:103], v[90:91], v[218:219]
	v_pk_mul_f32 v[84:85], v[84:85], v[238:239] op_sel_hi:[1,0]
	v_pk_mul_f32 v[86:87], v[86:87], v[238:239] op_sel_hi:[1,0]
	v_pk_fma_f32 v[84:85], v[96:97], v[84:85], v[220:221]
	v_pk_fma_f32 v[86:87], v[98:99], v[86:87], v[222:223]
	v_pk_mul_f32 v[80:81], v[80:81], v[238:239] op_sel_hi:[1,0]
	v_pk_mul_f32 v[82:83], v[82:83], v[238:239] op_sel_hi:[1,0]
	v_pk_fma_f32 v[80:81], v[108:109], v[80:81], v[224:225]
	v_pk_fma_f32 v[82:83], v[110:111], v[82:83], v[226:227]
	v_pk_mul_f32 v[240:241], v[92:93], v[92:93]
	v_pk_fma_f32 v[240:241], v[94:95], v[94:95], v[240:241]
	v_pk_fma_f32 v[240:241], v[88:89], v[88:89], v[240:241]
	v_pk_fma_f32 v[240:241], v[90:91], v[90:91], v[240:241]
	v_pk_fma_f32 v[240:241], v[84:85], v[84:85], v[240:241]
	v_pk_fma_f32 v[240:241], v[86:87], v[86:87], v[240:241]
	v_pk_fma_f32 v[240:241], v[80:81], v[80:81], v[240:241]
	v_pk_fma_f32 v[240:241], v[82:83], v[82:83], v[240:241]
	v_add_f32_e32 v240, v240, v241
	v_add_u32_e32 v245, 32, v194
	v_lshl_add_u32 v245, v245, 4, s51
	v_add_f32_dpp v240, v240, v240 quad_perm:[1,0,3,2] row_mask:0xf bank_mask:0xf
	s_nop 1
	v_add_f32_dpp v240, v240, v240 quad_perm:[2,3,0,1] row_mask:0xf bank_mask:0xf
	ds_write_b32 v245, v240
	v_add_u32_e32 v242, 144, v195
	v_lshlrev_b32_e32 v243, 2, v242
	v_lshl_add_u32 v244, v242, 13, v156
	global_load_dword v234, v243, s[10:11]
	global_load_dword v235, v243, s[86:87]
	global_load_dword v236, v243, s[88:89]
	global_load_dwordx4 v[212:215], v244, s[64:65] nt
	global_load_dwordx4 v[216:219], v244, s[64:65] offset:64 nt
	global_load_dwordx4 v[220:223], v244, s[64:65] offset:512 nt
	global_load_dwordx4 v[224:227], v244, s[64:65] offset:576 nt
	s_waitcnt vmcnt(14)
	v_add_f32_e32 v238, v228, v229
	v_add_f32_e32 v238, v238, v230
	v_fmamk_f32 v238, v238, 0x3a2aaaab, v183
	v_rsq_f32_e32 v238, v238
	s_nop 0
	v_pk_mul_f32 v[76:77], v[76:77], v[238:239] op_sel_hi:[1,0]
	v_pk_mul_f32 v[78:79], v[78:79], v[238:239] op_sel_hi:[1,0]
	v_pk_fma_f32 v[76:77], v[104:105], v[76:77], v[160:161]
	v_pk_fma_f32 v[78:79], v[106:107], v[78:79], v[162:163]
	v_pk_mul_f32 v[72:73], v[72:73], v[238:239] op_sel_hi:[1,0]
	v_pk_mul_f32 v[74:75], v[74:75], v[238:239] op_sel_hi:[1,0]
	v_pk_fma_f32 v[72:73], v[100:101], v[72:73], v[164:165]
	v_pk_fma_f32 v[74:75], v[102:103], v[74:75], v[166:167]
	v_pk_mul_f32 v[68:69], v[68:69], v[238:239] op_sel_hi:[1,0]
	v_pk_mul_f32 v[70:71], v[70:71], v[238:239] op_sel_hi:[1,0]
	v_pk_fma_f32 v[68:69], v[96:97], v[68:69], v[168:169]
	v_pk_fma_f32 v[70:71], v[98:99], v[70:71], v[170:171]
	v_pk_mul_f32 v[64:65], v[64:65], v[238:239] op_sel_hi:[1,0]
	v_pk_mul_f32 v[66:67], v[66:67], v[238:239] op_sel_hi:[1,0]
	v_pk_fma_f32 v[64:65], v[108:109], v[64:65], v[172:173]
	v_pk_fma_f32 v[66:67], v[110:111], v[66:67], v[174:175]
	v_pk_mul_f32 v[240:241], v[76:77], v[76:77]
	v_pk_fma_f32 v[240:241], v[78:79], v[78:79], v[240:241]
	v_pk_fma_f32 v[240:241], v[72:73], v[72:73], v[240:241]
	v_pk_fma_f32 v[240:241], v[74:75], v[74:75], v[240:241]
	v_pk_fma_f32 v[240:241], v[68:69], v[68:69], v[240:241]
	v_pk_fma_f32 v[240:241], v[70:71], v[70:71], v[240:241]
	v_pk_fma_f32 v[240:241], v[64:65], v[64:65], v[240:241]
	v_pk_fma_f32 v[240:241], v[66:67], v[66:67], v[240:241]
	v_add_f32_e32 v240, v240, v241
	v_add_u32_e32 v245, 48, v194
	v_lshl_add_u32 v245, v245, 4, s51
	v_add_f32_dpp v240, v240, v240 quad_perm:[1,0,3,2] row_mask:0xf bank_mask:0xf
	s_nop 1
	v_add_f32_dpp v240, v240, v240 quad_perm:[2,3,0,1] row_mask:0xf bank_mask:0xf
	ds_write_b32 v245, v240
	v_add_u32_e32 v242, 160, v195
	v_lshlrev_b32_e32 v243, 2, v242
	v_lshl_add_u32 v244, v242, 13, v156
	global_load_dword v228, v243, s[10:11]
	global_load_dword v229, v243, s[86:87]
	global_load_dword v230, v243, s[88:89]
	global_load_dwordx4 v[160:163], v244, s[64:65] nt
	global_load_dwordx4 v[164:167], v244, s[64:65] offset:64 nt
	global_load_dwordx4 v[168:171], v244, s[64:65] offset:512 nt
	global_load_dwordx4 v[172:175], v244, s[64:65] offset:576 nt
	s_waitcnt vmcnt(14)
	v_add_f32_e32 v238, v231, v232
	v_add_f32_e32 v238, v238, v233
	v_fmamk_f32 v238, v238, 0x3a2aaaab, v183
	v_rsq_f32_e32 v238, v238
	s_nop 0
	v_pk_mul_f32 v[60:61], v[60:61], v[238:239] op_sel_hi:[1,0]
	v_pk_mul_f32 v[62:63], v[62:63], v[238:239] op_sel_hi:[1,0]
	v_pk_fma_f32 v[60:61], v[104:105], v[60:61], v[196:197]
	v_pk_fma_f32 v[62:63], v[106:107], v[62:63], v[198:199]
	v_pk_mul_f32 v[56:57], v[56:57], v[238:239] op_sel_hi:[1,0]
	v_pk_mul_f32 v[58:59], v[58:59], v[238:239] op_sel_hi:[1,0]
	v_pk_fma_f32 v[56:57], v[100:101], v[56:57], v[200:201]
	v_pk_fma_f32 v[58:59], v[102:103], v[58:59], v[202:203]
	v_pk_mul_f32 v[52:53], v[52:53], v[238:239] op_sel_hi:[1,0]
	v_pk_mul_f32 v[54:55], v[54:55], v[238:239] op_sel_hi:[1,0]
	v_pk_fma_f32 v[52:53], v[96:97], v[52:53], v[204:205]
	v_pk_fma_f32 v[54:55], v[98:99], v[54:55], v[206:207]
	v_pk_mul_f32 v[48:49], v[48:49], v[238:239] op_sel_hi:[1,0]
	v_pk_mul_f32 v[50:51], v[50:51], v[238:239] op_sel_hi:[1,0]
	v_pk_fma_f32 v[48:49], v[108:109], v[48:49], v[208:209]
	v_pk_fma_f32 v[50:51], v[110:111], v[50:51], v[210:211]
	v_pk_mul_f32 v[240:241], v[60:61], v[60:61]
	v_pk_fma_f32 v[240:241], v[62:63], v[62:63], v[240:241]
	v_pk_fma_f32 v[240:241], v[56:57], v[56:57], v[240:241]
	v_pk_fma_f32 v[240:241], v[58:59], v[58:59], v[240:241]
	v_pk_fma_f32 v[240:241], v[52:53], v[52:53], v[240:241]
	v_pk_fma_f32 v[240:241], v[54:55], v[54:55], v[240:241]
	v_pk_fma_f32 v[240:241], v[48:49], v[48:49], v[240:241]
	v_pk_fma_f32 v[240:241], v[50:51], v[50:51], v[240:241]
	v_add_f32_e32 v240, v240, v241
	v_add_u32_e32 v245, 128, v194
	v_lshl_add_u32 v245, v245, 4, s51
	v_add_f32_dpp v240, v240, v240 quad_perm:[1,0,3,2] row_mask:0xf bank_mask:0xf
	s_nop 1
	v_add_f32_dpp v240, v240, v240 quad_perm:[2,3,0,1] row_mask:0xf bank_mask:0xf
	ds_write_b32 v245, v240
	v_add_u32_e32 v242, 176, v195
	v_lshlrev_b32_e32 v243, 2, v242
	v_lshl_add_u32 v244, v242, 13, v156
	global_load_dword v231, v243, s[10:11]
	global_load_dword v232, v243, s[86:87]
	global_load_dword v233, v243, s[88:89]
	global_load_dwordx4 v[196:199], v244, s[64:65] nt
	global_load_dwordx4 v[200:203], v244, s[64:65] offset:64 nt
	global_load_dwordx4 v[204:207], v244, s[64:65] offset:512 nt
	global_load_dwordx4 v[208:211], v244, s[64:65] offset:576 nt
	s_waitcnt vmcnt(14)
	v_add_f32_e32 v238, v234, v235
	v_add_f32_e32 v238, v238, v236
	v_fmamk_f32 v238, v238, 0x3a2aaaab, v183
	v_rsq_f32_e32 v238, v238
	s_nop 0
	v_pk_mul_f32 v[44:45], v[44:45], v[238:239] op_sel_hi:[1,0]
	v_pk_mul_f32 v[46:47], v[46:47], v[238:239] op_sel_hi:[1,0]
	v_pk_fma_f32 v[44:45], v[104:105], v[44:45], v[212:213]
	v_pk_fma_f32 v[46:47], v[106:107], v[46:47], v[214:215]
	v_pk_mul_f32 v[40:41], v[40:41], v[238:239] op_sel_hi:[1,0]
	v_pk_mul_f32 v[42:43], v[42:43], v[238:239] op_sel_hi:[1,0]
	v_pk_fma_f32 v[40:41], v[100:101], v[40:41], v[216:217]
	v_pk_fma_f32 v[42:43], v[102:103], v[42:43], v[218:219]
	v_pk_mul_f32 v[36:37], v[36:37], v[238:239] op_sel_hi:[1,0]
	v_pk_mul_f32 v[38:39], v[38:39], v[238:239] op_sel_hi:[1,0]
	v_pk_fma_f32 v[36:37], v[96:97], v[36:37], v[220:221]
	v_pk_fma_f32 v[38:39], v[98:99], v[38:39], v[222:223]
	v_pk_mul_f32 v[32:33], v[32:33], v[238:239] op_sel_hi:[1,0]
	v_pk_mul_f32 v[34:35], v[34:35], v[238:239] op_sel_hi:[1,0]
	v_pk_fma_f32 v[32:33], v[108:109], v[32:33], v[224:225]
	v_pk_fma_f32 v[34:35], v[110:111], v[34:35], v[226:227]
	v_pk_mul_f32 v[240:241], v[44:45], v[44:45]
	v_pk_fma_f32 v[240:241], v[46:47], v[46:47], v[240:241]
	v_pk_fma_f32 v[240:241], v[40:41], v[40:41], v[240:241]
	v_pk_fma_f32 v[240:241], v[42:43], v[42:43], v[240:241]
	v_pk_fma_f32 v[240:241], v[36:37], v[36:37], v[240:241]
	v_pk_fma_f32 v[240:241], v[38:39], v[38:39], v[240:241]
	v_pk_fma_f32 v[240:241], v[32:33], v[32:33], v[240:241]
	v_pk_fma_f32 v[240:241], v[34:35], v[34:35], v[240:241]
	v_add_f32_e32 v240, v240, v241
	v_add_u32_e32 v245, 144, v194
	v_lshl_add_u32 v245, v245, 4, s51
	v_add_f32_dpp v240, v240, v240 quad_perm:[1,0,3,2] row_mask:0xf bank_mask:0xf
	s_nop 1
	v_add_f32_dpp v240, v240, v240 quad_perm:[2,3,0,1] row_mask:0xf bank_mask:0xf
	ds_write_b32 v245, v240
	global_load_dwordx4 v[212:215], v156, s[58:59]
	global_load_dwordx4 v[216:219], v156, s[58:59] offset:64
	global_load_dwordx4 v[220:223], v156, s[58:59] offset:512
	global_load_dwordx4 v[224:227], v156, s[58:59] offset:576
	s_waitcnt vmcnt(11)
	v_add_f32_e32 v238, v228, v229
	v_add_f32_e32 v238, v238, v230
	v_fmamk_f32 v238, v238, 0x3a2aaaab, v183
	v_rsq_f32_e32 v238, v238
	s_nop 0
	v_pk_mul_f32 v[28:29], v[28:29], v[238:239] op_sel_hi:[1,0]
	v_pk_mul_f32 v[30:31], v[30:31], v[238:239] op_sel_hi:[1,0]
	v_pk_fma_f32 v[28:29], v[104:105], v[28:29], v[160:161]
	v_pk_fma_f32 v[30:31], v[106:107], v[30:31], v[162:163]
	v_pk_mul_f32 v[24:25], v[24:25], v[238:239] op_sel_hi:[1,0]
	v_pk_mul_f32 v[26:27], v[26:27], v[238:239] op_sel_hi:[1,0]
	v_pk_fma_f32 v[24:25], v[100:101], v[24:25], v[164:165]
	v_pk_fma_f32 v[26:27], v[102:103], v[26:27], v[166:167]
	v_pk_mul_f32 v[20:21], v[20:21], v[238:239] op_sel_hi:[1,0]
	v_pk_mul_f32 v[22:23], v[22:23], v[238:239] op_sel_hi:[1,0]
	v_pk_fma_f32 v[20:21], v[96:97], v[20:21], v[168:169]
	v_pk_fma_f32 v[22:23], v[98:99], v[22:23], v[170:171]
	v_pk_mul_f32 v[16:17], v[16:17], v[238:239] op_sel_hi:[1,0]
	v_pk_mul_f32 v[18:19], v[18:19], v[238:239] op_sel_hi:[1,0]
	v_pk_fma_f32 v[16:17], v[108:109], v[16:17], v[172:173]
	v_pk_fma_f32 v[18:19], v[110:111], v[18:19], v[174:175]
	v_pk_mul_f32 v[240:241], v[28:29], v[28:29]
	v_pk_fma_f32 v[240:241], v[30:31], v[30:31], v[240:241]
	v_pk_fma_f32 v[240:241], v[24:25], v[24:25], v[240:241]
	v_pk_fma_f32 v[240:241], v[26:27], v[26:27], v[240:241]
	v_pk_fma_f32 v[240:241], v[20:21], v[20:21], v[240:241]
	v_pk_fma_f32 v[240:241], v[22:23], v[22:23], v[240:241]
	v_pk_fma_f32 v[240:241], v[16:17], v[16:17], v[240:241]
	v_pk_fma_f32 v[240:241], v[18:19], v[18:19], v[240:241]
	v_add_f32_e32 v240, v240, v241
	v_add_u32_e32 v245, 160, v194
	v_lshl_add_u32 v245, v245, 4, s51
	v_add_f32_dpp v240, v240, v240 quad_perm:[1,0,3,2] row_mask:0xf bank_mask:0xf
	s_nop 1
	v_add_f32_dpp v240, v240, v240 quad_perm:[2,3,0,1] row_mask:0xf bank_mask:0xf
	ds_write_b32 v245, v240
	s_waitcnt vmcnt(4)
	v_add_f32_e32 v238, v231, v232
	v_add_f32_e32 v238, v238, v233
	v_fmamk_f32 v238, v238, 0x3a2aaaab, v183
	v_rsq_f32_e32 v238, v238
	s_nop 0
	v_pk_mul_f32 v[12:13], v[12:13], v[238:239] op_sel_hi:[1,0]
	v_pk_mul_f32 v[14:15], v[14:15], v[238:239] op_sel_hi:[1,0]
	v_pk_fma_f32 v[12:13], v[104:105], v[12:13], v[196:197]
	v_pk_fma_f32 v[14:15], v[106:107], v[14:15], v[198:199]
	v_pk_mul_f32 v[8:9], v[8:9], v[238:239] op_sel_hi:[1,0]
	v_pk_mul_f32 v[10:11], v[10:11], v[238:239] op_sel_hi:[1,0]
	v_pk_fma_f32 v[8:9], v[100:101], v[8:9], v[200:201]
	v_pk_fma_f32 v[10:11], v[102:103], v[10:11], v[202:203]
	v_pk_mul_f32 v[4:5], v[4:5], v[238:239] op_sel_hi:[1,0]
	v_pk_mul_f32 v[6:7], v[6:7], v[238:239] op_sel_hi:[1,0]
	v_pk_fma_f32 v[4:5], v[96:97], v[4:5], v[204:205]
	v_pk_fma_f32 v[6:7], v[98:99], v[6:7], v[206:207]
	v_pk_mul_f32 v[0:1], v[0:1], v[238:239] op_sel_hi:[1,0]
	v_pk_mul_f32 v[2:3], v[2:3], v[238:239] op_sel_hi:[1,0]
	v_pk_fma_f32 v[0:1], v[108:109], v[0:1], v[208:209]
	v_pk_fma_f32 v[2:3], v[110:111], v[2:3], v[210:211]
	v_pk_mul_f32 v[240:241], v[12:13], v[12:13]
	v_pk_fma_f32 v[240:241], v[14:15], v[14:15], v[240:241]
	v_pk_fma_f32 v[240:241], v[8:9], v[8:9], v[240:241]
	v_pk_fma_f32 v[240:241], v[10:11], v[10:11], v[240:241]
	v_pk_fma_f32 v[240:241], v[4:5], v[4:5], v[240:241]
	v_pk_fma_f32 v[240:241], v[6:7], v[6:7], v[240:241]
	v_pk_fma_f32 v[240:241], v[0:1], v[0:1], v[240:241]
	v_pk_fma_f32 v[240:241], v[2:3], v[2:3], v[240:241]
	v_add_f32_e32 v240, v240, v241
	v_add_u32_e32 v245, 176, v194
	v_lshl_add_u32 v245, v245, 4, s51
	v_add_f32_dpp v240, v240, v240 quad_perm:[1,0,3,2] row_mask:0xf bank_mask:0xf
	s_nop 1
	v_add_f32_dpp v240, v240, v240 quad_perm:[2,3,0,1] row_mask:0xf bank_mask:0xf
	ds_write_b32 v245, v240
	s_waitcnt lgkmcnt(0)
	s_barrier
	v_add_u32_e32 v98, s52, v185
	v_cndmask_b32_e64 v96, 0, 1, s[18:19]
	v_cmp_ne_u32_e64 s[2:3], 1, v96
	v_add_u32_e32 v96, s26, v98
	s_andn2_b64 vcc, exec, s[18:19]
	s_waitcnt lgkmcnt(0)
	v_ashrrev_i32_e32 v97, 31, v96
	s_cbranch_vccnz .LBB0_553
	v_lshl_add_u32 v99, v98, 4, 0
	v_add_u32_e32 v99, 0x20000, v99
	ds_read_b128 v[100:103], v99
	v_lshlrev_b64 v[104:105], 5, v[96:97]
	v_cmp_eq_u32_e32 vcc, 0, v185
	s_waitcnt lgkmcnt(0)
	v_mov_b32_e32 v106, v101
	v_mov_b32_e32 v107, v102
	v_mov_b32_e32 v101, v103
	v_pk_add_f32 v[100:101], v[106:107], v[100:101]
	v_lshl_add_u64 v[102:103], s[16:17], 0, v[104:105]
	v_pk_add_f32 v[100:101], v[100:101], v[100:101] op_sel:[0,1] op_sel_hi:[1,0]
	v_or_b32_e32 v100, 1, v100
	global_store_dword v[102:103], v100, off sc1
.LBB0_553:
	s_branch .LBB0_563
.LBB0_563:
	s_waitcnt lgkmcnt(0)
	s_barrier
	s_and_b64 vcc, exec, s[2:3]
	s_cbranch_vccnz .LBB0_565
	v_lshlrev_b64 v[96:97], 5, v[96:97]
	v_lshl_add_u64 v[96:97], s[12:13], 0, v[96:97]
	s_movk_i32 s100, 0x1000
	s_sleep 4
.Lp6_slot_poll:
	global_load_dwordx4 v[100:103], v[96:97], off sc1
	global_load_dwordx4 v[104:107], v[96:97], off offset:16 sc1
	s_waitcnt vmcnt(0)
	v_min_u32_e32 v99, v100, v101
	v_min3_u32 v99, v99, v102, v103
	v_min3_u32 v99, v99, v104, v105
	v_min3_u32 v99, v99, v106, v107
	v_cmp_eq_u32_e32 vcc, 0, v99
	s_cbranch_vccz .Lp6_slot_ready
	s_sub_u32 s100, s100, 1
	s_cmp_eq_u32 s100, 0
	s_cbranch_scc1 .Lp6_slot_ready
	s_sleep 1
	s_branch .Lp6_slot_poll
.Lp6_slot_ready:
	v_add_f32_e32 v97, 0, v100
	v_add_f32_e32 v97, v97, v101
	v_add_f32_e32 v97, v97, v102
	v_add_f32_e32 v97, v97, v103
	v_add_f32_e32 v97, v97, v104
	v_add_f32_e32 v97, v97, v105
	v_add_f32_e32 v97, v97, v106
	v_add_f32_e32 v96, v97, v107
	v_fmamk_f32 v96, v96, 0x3a000000, v183
	v_rsq_f32_e32 v96, v96
	v_lshl_add_u32 v97, v98, 2, 0
	v_add_u32_e32 v97, 0x21000, v97
	ds_write_b32 v97, v96
